# also nt: the prompt memory K/V loads of the cross-attention (each XCD reads them once)
# baseline (speedup 1.0000x reference)
.LBB0_935:
	s_andn2_b64 vcc, exec, s[4:5]
	v_lshlrev_b32_e32 v194, 1, v3
	s_cbranch_vccnz .LBB0_937
	v_readlane_b32 s3, v255, 5
	s_nop 1
	v_add_u32_e32 v0, s3, v0
	v_ashrrev_i32_e32 v1, 31, v0
	v_lshlrev_b64 v[0:1], 10, v[0:1]
	v_readlane_b32 s3, v255, 7
	v_lshl_add_u64 v[0:1], s[8:9], 0, v[0:1]
	s_lshl_b32 s92, s3, 1
	v_lshl_add_u64 v[0:1], v[0:1], 0, s[92:93]
	v_lshl_add_u64 v[0:1], v[0:1], 0, v[194:195]
	global_load_dwordx4 v[96:99], v[0:1], off nt
	global_load_dwordx4 v[100:103], v[0:1], off offset:512 nt

.LBB0_939:
	s_andn2_b64 vcc, exec, s[14:15]
	s_cbranch_vccnz .LBB0_941
	v_readlane_b32 s3, v255, 5
	s_nop 1
	v_add_u32_e32 v2, s3, v2
	v_ashrrev_i32_e32 v3, 31, v2
	v_lshlrev_b64 v[2:3], 10, v[2:3]
	v_readlane_b32 s3, v255, 7
	v_lshl_add_u64 v[2:3], s[8:9], 0, v[2:3]
	s_lshl_b32 s92, s3, 1
	v_lshl_add_u64 v[2:3], v[2:3], 0, s[92:93]
	v_lshl_add_u64 v[2:3], v[2:3], 0, v[194:195]
	global_load_dwordx4 v[104:107], v[2:3], off nt
	global_load_dwordx4 v[108:111], v[2:3], off offset:512 nt

.LBB0_943:
	s_andn2_b64 vcc, exec, s[14:15]
	s_cbranch_vccnz .LBB0_945
	v_readlane_b32 s3, v255, 5
	s_nop 1
	v_add_u32_e32 v2, s3, v2
	v_ashrrev_i32_e32 v3, 31, v2
	v_lshlrev_b64 v[2:3], 10, v[2:3]
	v_readlane_b32 s3, v255, 7
	v_lshl_add_u64 v[2:3], s[8:9], 0, v[2:3]
	s_lshl_b32 s92, s3, 1
	v_lshl_add_u64 v[2:3], v[2:3], 0, s[92:93]
	v_lshl_add_u64 v[2:3], v[2:3], 0, v[194:195]
	global_load_dwordx4 v[112:115], v[2:3], off nt
	global_load_dwordx4 v[132:135], v[2:3], off offset:512 nt

.LBB0_947:
	s_mov_b32 s3, 1
	s_andn2_b64 vcc, exec, s[4:5]
	v_readlane_b32 s4, v254, 46
	s_cbranch_vccnz .LBB0_949
	v_readlane_b32 s3, v255, 5
	v_readlane_b32 s4, v254, 45
	s_nop 0
	v_add_u32_e32 v0, s3, v2
	v_ashrrev_i32_e32 v1, 31, v0
	v_lshlrev_b64 v[0:1], 10, v[0:1]
	v_readlane_b32 s3, v255, 7
	v_lshl_add_u64 v[0:1], s[8:9], 0, v[0:1]
	s_lshl_b32 s92, s3, 1
	v_lshl_add_u64 v[0:1], v[0:1], 0, s[92:93]
	v_lshl_add_u64 v[0:1], v[0:1], 0, v[194:195]
	global_load_dwordx4 v[136:139], v[0:1], off nt
	global_load_dwordx4 v[140:143], v[0:1], off offset:512 nt
	s_mov_b32 s3, 8
